# DPP instead of LDS round trips: xor-1/2/4/8 butterfly steps of the LN and merge row reductions as v_add_f32_dpp (quad_perm / row_half_mirror / row_mirror)
# speedup vs baseline: 1.0105x; 1.0098x over previous
.LBB0_86:
	s_or_b64 exec, exec, s[54:55]
	s_and_saveexec_b64 s[0:1], s[52:53]
	s_cbranch_execz .LBB0_95
	s_movk_i32 s14, 0x100
	v_cmp_gt_i32_e32 vcc, s14, v137
	v_mov_b32_e32 v0, s29
	v_mov_b32_e32 v98, s9
	v_cndmask_b32_e32 v99, v0, v98, vcc
	v_mov_b32_e32 v0, s28
	v_mov_b32_e32 v98, s8
	v_cndmask_b32_e32 v98, v0, v98, vcc
	v_cndmask_b32_e64 v0, 23, 20, vcc
	v_lshlrev_b64 v[104:105], v0, v[182:183]
	v_cndmask_b32_e32 v101, 0, v141, vcc
	v_cndmask_b32_e32 v100, v139, v137, vcc
	v_lshl_add_u64 v[98:99], v[98:99], 0, v[104:105]
	v_lshlrev_b64 v[100:101], 12, v[100:101]
	v_add_f32_dpp v0, v102, v102 quad_perm:[1,0,3,2] row_mask:0xf bank_mask:0xf
	v_lshl_add_u64 v[128:129], v[98:99], 0, v[100:101]
	v_mov_b32_e32 v177, v1
	s_mov_b64 s[52:53], -1
	v_add_f32_dpp v0, v0, v0 quad_perm:[2,3,0,1] row_mask:0xf bank_mask:0xf
	s_nop 1
	v_add_f32_dpp v0, v0, v0 row_half_mirror row_mask:0xf bank_mask:0xf
	s_nop 1
	v_add_f32_dpp v0, v0, v0 row_mirror row_mask:0xf bank_mask:0xf
	ds_bpermute_b32 v102, v186, v0
	s_waitcnt lgkmcnt(0)
	v_add_f32_e32 v0, v0, v102
	ds_bpermute_b32 v102, v187, v0
	s_waitcnt lgkmcnt(0)
	v_add_f32_e32 v0, v0, v102
	v_mul_f32_e32 v0, 0x3a800000, v0
	v_pk_add_f32 v[98:99], v[146:147], v[0:1] op_sel_hi:[1,0] neg_lo:[0,1] neg_hi:[0,1]
	v_pk_add_f32 v[182:183], v[152:153], v[0:1] op_sel_hi:[1,0] neg_lo:[0,1] neg_hi:[0,1]
	v_pk_mul_f32 v[100:101], v[98:99], v[98:99]
	v_pk_add_f32 v[116:117], v[154:155], v[0:1] op_sel_hi:[1,0] neg_lo:[0,1] neg_hi:[0,1]
	v_pk_add_f32 v[112:113], v[160:161], v[0:1] op_sel_hi:[1,0] neg_lo:[0,1] neg_hi:[0,1]
	v_pk_add_f32 v[108:109], v[164:165], v[0:1] op_sel_hi:[1,0] neg_lo:[0,1] neg_hi:[0,1]
	v_pk_add_f32 v[110:111], v[168:169], v[0:1] op_sel_hi:[1,0] neg_lo:[0,1] neg_hi:[0,1]
	v_pk_add_f32 v[106:107], v[172:173], v[0:1] op_sel_hi:[1,0] neg_lo:[0,1] neg_hi:[0,1]
	v_pk_add_f32 v[104:105], v[174:175], v[0:1] op_sel_hi:[1,0] neg_lo:[0,1] neg_hi:[0,1]
	v_pk_mul_f32 v[192:193], v[182:183], v[182:183]
	v_add_f32_e32 v0, v100, v101
	v_add_f32_e32 v0, v192, v0
	v_pk_mul_f32 v[114:115], v[116:117], v[116:117]
	v_add_f32_e32 v0, v193, v0
	v_add_f32_e32 v0, v114, v0
	v_pk_mul_f32 v[118:119], v[112:113], v[112:113]
	v_add_f32_e32 v0, v115, v0
	v_add_f32_e32 v0, v118, v0
	v_pk_mul_f32 v[120:121], v[108:109], v[108:109]
	v_add_f32_e32 v0, v119, v0
	v_add_f32_e32 v0, v120, v0
	v_pk_mul_f32 v[122:123], v[110:111], v[110:111]
	v_add_f32_e32 v0, v121, v0
	v_add_f32_e32 v0, v122, v0
	v_pk_mul_f32 v[124:125], v[106:107], v[106:107]
	v_add_f32_e32 v0, v123, v0
	v_add_f32_e32 v0, v124, v0
	v_pk_mul_f32 v[126:127], v[104:105], v[104:105]
	v_add_f32_e32 v0, v125, v0
	v_add_f32_e32 v0, v126, v0
	v_add_f32_e32 v0, v127, v0
	v_lshl_add_u64 v[120:121], v[128:129], 0, v[176:177]
	s_nop 0
	v_add_f32_dpp v0, v0, v0 quad_perm:[1,0,3,2] row_mask:0xf bank_mask:0xf
	s_nop 1
	v_add_f32_dpp v0, v0, v0 quad_perm:[2,3,0,1] row_mask:0xf bank_mask:0xf
	s_nop 1
	v_add_f32_dpp v0, v0, v0 row_half_mirror row_mask:0xf bank_mask:0xf
	s_nop 1
	v_add_f32_dpp v0, v0, v0 row_mirror row_mask:0xf bank_mask:0xf
	ds_bpermute_b32 v100, v186, v0
	s_waitcnt lgkmcnt(0)
	v_add_f32_e32 v0, v0, v100
	ds_bpermute_b32 v100, v187, v0
	s_waitcnt lgkmcnt(0)
	v_add_f32_e32 v0, v0, v100
	v_mov_b32_e32 v100, 0x3727c5ac
	v_fmamk_f32 v0, v0, 0x3a800000, v100
	v_cmp_gt_f32_e32 vcc, s31, v0
	v_mul_f32_e32 v100, 0x4b800000, v0
	s_nop 0
	v_cndmask_b32_e32 v0, v0, v100, vcc
	v_rsq_f32_e32 v0, v0
	s_nop 0
	v_mul_f32_e32 v100, 0x45800000, v0
	v_cndmask_b32_e32 v114, v0, v100, vcc
	v_mov_b32_e32 v118, v114
	v_mov_b32_e32 v119, v114
	v_pk_mul_f32 v[98:99], v[98:99], v[114:115] op_sel_hi:[1,0]
	v_pk_mul_f32 v[100:101], v[182:183], v[114:115] op_sel_hi:[1,0]
	s_waitcnt vmcnt(0)
	v_pk_fma_f32 v[98:99], v[30:31], v[98:99], v[22:23]
	v_pk_fma_f32 v[100:101], v[32:33], v[100:101], v[24:25]
	s_and_b64 vcc, exec, s[42:43]
	v_pk_mul_f32 v[122:123], v[116:117], v[118:119]
	global_store_dwordx4 v[120:121], v[98:101], off
	s_cbranch_vccz .LBB0_89
	v_mov_b32_e32 v115, v114
	v_pk_mul_f32 v[116:117], v[112:113], v[114:115]
	v_pk_fma_f32 v[124:125], v[26:27], v[122:123], v[18:19]
	v_pk_fma_f32 v[126:127], v[28:29], v[116:117], v[20:21]
	global_store_dwordx4 v[120:121], v[124:127], off offset:1024
	s_mov_b64 s[52:53], 0

.LBB0_95:
	s_or_b64 exec, exec, s[0:1]
	s_and_saveexec_b64 s[0:1], s[50:51]
	s_cbranch_execz .LBB0_61
	s_movk_i32 s14, 0x100
	v_cmp_gt_i32_e32 vcc, s14, v135
	v_mov_b32_e32 v98, s29
	v_mov_b32_e32 v99, s9
	v_ashrrev_i32_e32 v0, 31, v135
	v_cndmask_b32_e32 v99, v98, v99, vcc
	v_mov_b32_e32 v98, s28
	v_mov_b32_e32 v101, s8
	v_ashrrev_i32_e32 v181, 31, v180
	v_cndmask_b32_e32 v98, v98, v101, vcc
	v_cndmask_b32_e32 v101, 0, v0, vcc
	v_cndmask_b32_e64 v0, 23, 20, vcc
	v_lshlrev_b64 v[104:105], v0, v[180:181]
	v_add_u32_e32 v100, 0xffffff00, v135
	v_cndmask_b32_e32 v100, v100, v135, vcc
	v_lshl_add_u64 v[98:99], v[98:99], 0, v[104:105]
	v_lshlrev_b64 v[100:101], 12, v[100:101]
	v_add_f32_dpp v0, v103, v103 quad_perm:[1,0,3,2] row_mask:0xf bank_mask:0xf
	v_lshl_add_u64 v[126:127], v[98:99], 0, v[100:101]
	v_mov_b32_e32 v177, v1
	s_mov_b64 s[50:51], -1
	v_add_f32_dpp v0, v0, v0 quad_perm:[2,3,0,1] row_mask:0xf bank_mask:0xf
	s_nop 1
	v_add_f32_dpp v0, v0, v0 row_half_mirror row_mask:0xf bank_mask:0xf
	s_nop 1
	v_add_f32_dpp v0, v0, v0 row_mirror row_mask:0xf bank_mask:0xf
	ds_bpermute_b32 v102, v186, v0
	s_waitcnt lgkmcnt(0)
	v_add_f32_e32 v0, v0, v102
	ds_bpermute_b32 v102, v187, v0
	s_waitcnt lgkmcnt(0)
	v_add_f32_e32 v0, v0, v102
	v_mul_f32_e32 v0, 0x3a800000, v0
	v_pk_add_f32 v[98:99], v[144:145], v[0:1] op_sel_hi:[1,0] neg_lo:[0,1] neg_hi:[0,1]
	v_pk_add_f32 v[128:129], v[148:149], v[0:1] op_sel_hi:[1,0] neg_lo:[0,1] neg_hi:[0,1]
	v_pk_mul_f32 v[100:101], v[98:99], v[98:99]
	v_pk_add_f32 v[114:115], v[150:151], v[0:1] op_sel_hi:[1,0] neg_lo:[0,1] neg_hi:[0,1]
	v_pk_add_f32 v[110:111], v[156:157], v[0:1] op_sel_hi:[1,0] neg_lo:[0,1] neg_hi:[0,1]
	v_pk_add_f32 v[106:107], v[158:159], v[0:1] op_sel_hi:[1,0] neg_lo:[0,1] neg_hi:[0,1]
	v_pk_add_f32 v[108:109], v[162:163], v[0:1] op_sel_hi:[1,0] neg_lo:[0,1] neg_hi:[0,1]
	v_pk_add_f32 v[104:105], v[166:167], v[0:1] op_sel_hi:[1,0] neg_lo:[0,1] neg_hi:[0,1]
	v_pk_add_f32 v[102:103], v[170:171], v[0:1] op_sel_hi:[1,0] neg_lo:[0,1] neg_hi:[0,1]
	v_pk_mul_f32 v[180:181], v[128:129], v[128:129]
	v_add_f32_e32 v0, v100, v101
	v_add_f32_e32 v0, v180, v0
	v_pk_mul_f32 v[112:113], v[114:115], v[114:115]
	v_add_f32_e32 v0, v181, v0
	v_add_f32_e32 v0, v112, v0
	v_pk_mul_f32 v[116:117], v[110:111], v[110:111]
	v_add_f32_e32 v0, v113, v0
	v_add_f32_e32 v0, v116, v0
	v_pk_mul_f32 v[118:119], v[106:107], v[106:107]
	v_add_f32_e32 v0, v117, v0
	v_add_f32_e32 v0, v118, v0
	v_pk_mul_f32 v[120:121], v[108:109], v[108:109]
	v_add_f32_e32 v0, v119, v0
	v_add_f32_e32 v0, v120, v0
	v_pk_mul_f32 v[122:123], v[104:105], v[104:105]
	v_add_f32_e32 v0, v121, v0
	v_add_f32_e32 v0, v122, v0
	v_pk_mul_f32 v[124:125], v[102:103], v[102:103]
	v_add_f32_e32 v0, v123, v0
	v_add_f32_e32 v0, v124, v0
	v_add_f32_e32 v0, v125, v0
	v_lshl_add_u64 v[118:119], v[126:127], 0, v[176:177]
	s_nop 0
	v_add_f32_dpp v0, v0, v0 quad_perm:[1,0,3,2] row_mask:0xf bank_mask:0xf
	s_nop 1
	v_add_f32_dpp v0, v0, v0 quad_perm:[2,3,0,1] row_mask:0xf bank_mask:0xf
	s_nop 1
	v_add_f32_dpp v0, v0, v0 row_half_mirror row_mask:0xf bank_mask:0xf
	s_nop 1
	v_add_f32_dpp v0, v0, v0 row_mirror row_mask:0xf bank_mask:0xf
	ds_bpermute_b32 v100, v186, v0
	s_waitcnt lgkmcnt(0)
	v_add_f32_e32 v0, v0, v100
	ds_bpermute_b32 v100, v187, v0
	s_waitcnt lgkmcnt(0)
	v_add_f32_e32 v0, v0, v100
	v_mov_b32_e32 v100, 0x3727c5ac
	v_fmamk_f32 v0, v0, 0x3a800000, v100
	v_cmp_gt_f32_e32 vcc, s31, v0
	v_mul_f32_e32 v100, 0x4b800000, v0
	s_nop 0
	v_cndmask_b32_e32 v0, v0, v100, vcc
	v_rsq_f32_e32 v0, v0
	s_nop 0
	v_mul_f32_e32 v100, 0x45800000, v0
	v_cndmask_b32_e32 v112, v0, v100, vcc
	v_mov_b32_e32 v116, v112
	v_mov_b32_e32 v117, v112
	v_pk_mul_f32 v[98:99], v[98:99], v[112:113] op_sel_hi:[1,0]
	v_pk_mul_f32 v[100:101], v[128:129], v[112:113] op_sel_hi:[1,0]
	s_waitcnt vmcnt(0)
	v_pk_fma_f32 v[98:99], v[30:31], v[98:99], v[22:23]
	v_pk_fma_f32 v[100:101], v[32:33], v[100:101], v[24:25]
	s_and_b64 vcc, exec, s[42:43]
	v_pk_mul_f32 v[120:121], v[114:115], v[116:117]
	global_store_dwordx4 v[118:119], v[98:101], off
	s_cbranch_vccz .LBB0_98
	v_mov_b32_e32 v113, v112
	v_pk_mul_f32 v[114:115], v[110:111], v[112:113]
	v_pk_fma_f32 v[122:123], v[26:27], v[120:121], v[18:19]
	v_pk_fma_f32 v[124:125], v[28:29], v[114:115], v[20:21]
	global_store_dwordx4 v[118:119], v[122:125], off offset:1024
	s_mov_b64 s[50:51], 0

.LBB0_152:
	s_or_b64 exec, exec, s[40:41]
	s_waitcnt vmcnt(0) lgkmcnt(0)
	v_lshlrev_b32_e32 v82, 16, v34
	v_and_b32_e32 v83, 0xffff0000, v34
	v_lshlrev_b32_e32 v84, 16, v38
	v_and_b32_e32 v85, 0xffff0000, v38
	v_lshlrev_b32_e32 v34, 16, v35
	v_and_b32_e32 v35, 0xffff0000, v35
	v_lshlrev_b32_e32 v38, 16, v39
	v_and_b32_e32 v39, 0xffff0000, v39
	v_pk_add_f32 v[82:83], v[82:83], v[84:85]
	v_pk_add_f32 v[34:35], v[34:35], v[38:39]
	v_lshlrev_b32_e32 v38, 16, v36
	v_and_b32_e32 v39, 0xffff0000, v36
	v_lshlrev_b32_e32 v84, 16, v40
	v_and_b32_e32 v85, 0xffff0000, v40
	v_lshlrev_b32_e32 v36, 16, v37
	v_and_b32_e32 v37, 0xffff0000, v37
	v_lshlrev_b32_e32 v40, 16, v41
	v_and_b32_e32 v41, 0xffff0000, v41
	v_pk_add_f32 v[38:39], v[38:39], v[84:85]
	v_pk_add_f32 v[36:37], v[36:37], v[40:41]
	v_lshlrev_b32_e32 v40, 16, v30
	v_and_b32_e32 v41, 0xffff0000, v30
	v_lshlrev_b32_e32 v84, 16, v26
	v_and_b32_e32 v85, 0xffff0000, v26
	v_lshlrev_b32_e32 v30, 16, v31
	v_and_b32_e32 v31, 0xffff0000, v31
	v_lshlrev_b32_e32 v26, 16, v27
	v_and_b32_e32 v27, 0xffff0000, v27
	v_pk_add_f32 v[40:41], v[40:41], v[84:85]
	v_pk_add_f32 v[26:27], v[30:31], v[26:27]
	v_lshlrev_b32_e32 v30, 16, v32
	v_and_b32_e32 v31, 0xffff0000, v32
	v_lshlrev_b32_e32 v84, 16, v28
	v_and_b32_e32 v85, 0xffff0000, v28
	v_lshlrev_b32_e32 v32, 16, v33
	v_and_b32_e32 v33, 0xffff0000, v33
	v_lshlrev_b32_e32 v28, 16, v29
	v_and_b32_e32 v29, 0xffff0000, v29
	v_pk_add_f32 v[28:29], v[32:33], v[28:29]
	v_pk_mul_f32 v[32:33], v[82:83], v[82:83]
	v_pk_add_f32 v[30:31], v[30:31], v[84:85]
	v_pk_mul_f32 v[84:85], v[34:35], v[34:35]
	v_add_f32_e32 v0, v32, v33
	v_add_f32_e32 v0, v84, v0
	v_pk_mul_f32 v[86:87], v[38:39], v[38:39]
	v_add_f32_e32 v0, v85, v0
	v_add_f32_e32 v0, v86, v0
	v_pk_mul_f32 v[88:89], v[36:37], v[36:37]
	v_add_f32_e32 v0, v87, v0
	v_add_f32_e32 v0, v88, v0
	v_pk_mul_f32 v[90:91], v[40:41], v[40:41]
	v_add_f32_e32 v0, v89, v0
	v_add_f32_e32 v0, v90, v0
	v_pk_mul_f32 v[92:93], v[26:27], v[26:27]
	v_add_f32_e32 v0, v91, v0
	v_add_f32_e32 v0, v92, v0
	v_pk_mul_f32 v[94:95], v[30:31], v[30:31]
	v_add_f32_e32 v0, v93, v0
	v_add_f32_e32 v0, v94, v0
	v_pk_mul_f32 v[96:97], v[28:29], v[28:29]
	v_add_f32_e32 v0, v95, v0
	v_add_f32_e32 v0, v96, v0
	v_add_f32_e32 v0, v97, v0
	v_lshlrev_b32_e32 v86, 16, v18
	v_and_b32_e32 v87, 0xffff0000, v18
	v_lshlrev_b32_e32 v32, 16, v22
	v_and_b32_e32 v33, 0xffff0000, v22
	v_add_f32_dpp v0, v0, v0 quad_perm:[1,0,3,2] row_mask:0xf bank_mask:0xf
	v_lshlrev_b32_e32 v88, 16, v19
	v_and_b32_e32 v89, 0xffff0000, v19
	v_mul_f32_e32 v19, 0xbfb8aa3b, v33
	v_exp_f32_e32 v19, v19
	v_add_f32_dpp v0, v0, v0 quad_perm:[2,3,0,1] row_mask:0xf bank_mask:0xf
	v_lshlrev_b32_e32 v22, 16, v23
	v_add_f32_e32 v19, 1.0, v19
	v_rcp_f32_e32 v19, v19
	v_and_b32_e32 v23, 0xffff0000, v23
	v_add_f32_dpp v0, v0, v0 row_half_mirror row_mask:0xf bank_mask:0xf
	v_lshlrev_b32_e32 v90, 16, v20
	v_and_b32_e32 v91, 0xffff0000, v20
	v_lshlrev_b32_e32 v92, 16, v21
	v_and_b32_e32 v93, 0xffff0000, v21
	v_add_f32_dpp v0, v0, v0 row_mirror row_mask:0xf bank_mask:0xf
	v_mov_b32_e32 v18, 0x358637bd
	v_fmamk_f32 v0, v0, 0x3b800000, v18
	v_mul_f32_e32 v18, 0x4b800000, v0
	v_cmp_gt_f32_e32 vcc, s31, v0
	v_lshlrev_b32_e32 v84, 16, v24
	v_and_b32_e32 v85, 0xffff0000, v24
	v_cndmask_b32_e32 v0, v0, v18, vcc
	v_mul_f32_e32 v18, 0xbfb8aa3b, v32
	v_exp_f32_e32 v18, v18
	v_rsq_f32_e32 v0, v0
	v_lshlrev_b32_e32 v24, 16, v25
	v_and_b32_e32 v25, 0xffff0000, v25
	v_add_f32_e32 v18, 1.0, v18
	v_rcp_f32_e32 v18, v18
	v_mul_f32_e32 v20, 0x45800000, v0
	v_cndmask_b32_e32 v0, v0, v20, vcc
	v_pk_mul_f32 v[20:21], v[82:83], v[0:1] op_sel_hi:[1,0]
	v_pk_mul_f32 v[18:19], v[18:19], v[32:33]
	v_mul_f32_e32 v32, 0xbfb8aa3b, v22
	v_mul_f32_e32 v33, 0xbfb8aa3b, v23
	v_exp_f32_e32 v32, v32
	v_exp_f32_e32 v33, v33
	v_pk_mul_f32 v[20:21], v[14:15], v[20:21]
	v_pk_mul_f32 v[26:27], v[26:27], v[0:1] op_sel_hi:[1,0]
	v_pk_mul_f32 v[18:19], v[18:19], v[20:21]
	v_add_f32_e32 v20, 1.0, v32
	v_add_f32_e32 v21, 1.0, v33
	v_rcp_f32_e32 v20, v20
	v_rcp_f32_e32 v21, v21
	v_cvt_pk_bf16_f32 v18, v18, v19
	v_mul_f32_e32 v19, 0xbfb8aa3b, v84
	v_exp_f32_e32 v19, v19
	v_pk_mul_f32 v[20:21], v[20:21], v[22:23]
	v_mul_f32_e32 v22, 0xbfb8aa3b, v85
	v_exp_f32_e32 v23, v22
	v_pk_mul_f32 v[32:33], v[34:35], v[0:1] op_sel_hi:[1,0]
	v_add_f32_e32 v19, 1.0, v19
	v_pk_mul_f32 v[32:33], v[16:17], v[32:33]
	v_rcp_f32_e32 v22, v19
	v_add_f32_e32 v19, 1.0, v23
	v_pk_mul_f32 v[20:21], v[20:21], v[32:33]
	v_rcp_f32_e32 v23, v19
	v_mul_f32_e32 v32, 0xbfb8aa3b, v24
	v_mul_f32_e32 v33, 0xbfb8aa3b, v25
	v_exp_f32_e32 v32, v32
	v_exp_f32_e32 v33, v33
	v_cvt_pk_bf16_f32 v19, v20, v21
	v_pk_mul_f32 v[20:21], v[38:39], v[0:1] op_sel_hi:[1,0]
	v_pk_mul_f32 v[22:23], v[22:23], v[84:85]
	v_pk_mul_f32 v[20:21], v[10:11], v[20:21]
	v_pk_mul_f32 v[26:27], v[8:9], v[26:27]
	v_pk_mul_f32 v[20:21], v[22:23], v[20:21]
	v_add_f32_e32 v22, 1.0, v32
	v_add_f32_e32 v23, 1.0, v33
	v_rcp_f32_e32 v22, v22
	v_rcp_f32_e32 v23, v23
	v_cvt_pk_bf16_f32 v20, v20, v21
	v_mul_f32_e32 v21, 0xbfb8aa3b, v86
	v_exp_f32_e32 v21, v21
	v_pk_mul_f32 v[22:23], v[22:23], v[24:25]
	v_mul_f32_e32 v24, 0xbfb8aa3b, v87
	v_exp_f32_e32 v25, v24
	v_add_f32_e32 v21, 1.0, v21
	v_pk_mul_f32 v[32:33], v[36:37], v[0:1] op_sel_hi:[1,0]
	v_rcp_f32_e32 v24, v21
	v_add_f32_e32 v21, 1.0, v25
	v_pk_mul_f32 v[32:33], v[12:13], v[32:33]
	v_rcp_f32_e32 v25, v21
	v_pk_mul_f32 v[22:23], v[22:23], v[32:33]
	v_mul_f32_e32 v32, 0xbfb8aa3b, v88
	v_mul_f32_e32 v33, 0xbfb8aa3b, v89
	v_exp_f32_e32 v32, v32
	v_exp_f32_e32 v33, v33
	v_cvt_pk_bf16_f32 v21, v22, v23
	v_pk_mul_f32 v[22:23], v[40:41], v[0:1] op_sel_hi:[1,0]
	v_pk_mul_f32 v[24:25], v[24:25], v[86:87]
	v_pk_mul_f32 v[22:23], v[6:7], v[22:23]
	v_pk_mul_f32 v[28:29], v[28:29], v[0:1] op_sel_hi:[1,0]
	v_pk_mul_f32 v[22:23], v[24:25], v[22:23]
	v_add_f32_e32 v24, 1.0, v32
	v_add_f32_e32 v25, 1.0, v33
	v_cvt_pk_bf16_f32 v22, v22, v23
	v_mul_f32_e32 v23, 0xbfb8aa3b, v90
	v_rcp_f32_e32 v24, v24
	v_rcp_f32_e32 v25, v25
	v_exp_f32_e32 v23, v23
	v_mul_f32_e32 v32, 0xbfb8aa3b, v91
	v_exp_f32_e32 v32, v32
	v_pk_mul_f32 v[24:25], v[24:25], v[88:89]
	v_add_f32_e32 v23, 1.0, v23
	v_pk_mul_f32 v[24:25], v[24:25], v[26:27]
	v_rcp_f32_e32 v26, v23
	v_add_f32_e32 v23, 1.0, v32
	v_rcp_f32_e32 v27, v23
	v_cvt_pk_bf16_f32 v23, v24, v25
	v_pk_mul_f32 v[24:25], v[30:31], v[0:1] op_sel_hi:[1,0]
	v_mul_f32_e32 v30, 0xbfb8aa3b, v92
	v_mul_f32_e32 v31, 0xbfb8aa3b, v93
	v_exp_f32_e32 v30, v30
	v_exp_f32_e32 v31, v31
	v_pk_mul_f32 v[24:25], v[2:3], v[24:25]
	v_pk_mul_f32 v[26:27], v[26:27], v[90:91]
	v_pk_mul_f32 v[28:29], v[4:5], v[28:29]
	v_pk_mul_f32 v[24:25], v[26:27], v[24:25]
	v_add_f32_e32 v26, 1.0, v30
	v_add_f32_e32 v27, 1.0, v31
	v_rcp_f32_e32 v26, v26
	v_rcp_f32_e32 v27, v27
	v_cvt_pk_bf16_f32 v24, v24, v25
	v_cmp_gt_i32_e32 vcc, s14, v62
	v_pk_mul_f32 v[26:27], v[26:27], v[92:93]
	s_nop 0
	v_pk_mul_f32 v[26:27], v[26:27], v[28:29]
	s_nop 0
	v_cvt_pk_bf16_f32 v25, v26, v27
	v_lshl_add_u64 v[26:27], v[44:45], 0, v[64:65]
	global_store_dwordx4 v[26:27], v[18:21], off
	global_store_dwordx4 v[26:27], v[22:25], off offset:16
	s_and_saveexec_b64 s[40:41], vcc
	s_cbranch_execz .LBB0_149
	v_pk_mul_f32 v[18:19], v[48:49], v[48:49]
	v_pk_mul_f32 v[20:21], v[52:53], v[52:53]
	v_add_f32_e32 v0, v19, v18
	v_add_f32_e32 v0, v20, v0
	v_pk_mul_f32 v[22:23], v[56:57], v[56:57]
	v_add_f32_e32 v0, v21, v0
	v_add_f32_e32 v0, v22, v0
	v_pk_mul_f32 v[24:25], v[60:61], v[60:61]
	v_add_f32_e32 v0, v23, v0
	v_add_f32_e32 v0, v24, v0
	v_pk_mul_f32 v[26:27], v[66:67], v[66:67]
	v_add_f32_e32 v0, v25, v0
	v_add_f32_e32 v0, v26, v0
	v_pk_mul_f32 v[28:29], v[70:71], v[70:71]
	v_add_f32_e32 v0, v27, v0
	v_add_f32_e32 v0, v28, v0
	v_pk_mul_f32 v[30:31], v[74:75], v[74:75]
	v_add_f32_e32 v0, v29, v0
	v_add_f32_e32 v0, v30, v0
	v_pk_mul_f32 v[32:33], v[78:79], v[78:79]
	v_add_f32_e32 v0, v31, v0
	v_add_f32_e32 v0, v32, v0
	v_add_f32_e32 v0, v33, v0
	v_mul_f32_e32 v19, 0xbfb8aa3b, v46
	v_mul_f32_e32 v20, 0xbfb8aa3b, v47
	v_exp_f32_e32 v19, v19
	v_exp_f32_e32 v20, v20
	v_add_f32_dpp v0, v0, v0 quad_perm:[1,0,3,2] row_mask:0xf bank_mask:0xf
	v_mul_f32_e32 v23, 0xbfb8aa3b, v51
	v_exp_f32_e32 v23, v23
	v_mul_f32_e32 v24, 0xbfb8aa3b, v55
	v_exp_f32_e32 v24, v24
	v_add_f32_dpp v0, v0, v0 quad_perm:[2,3,0,1] row_mask:0xf bank_mask:0xf
	v_mul_f32_e32 v25, 0xbfb8aa3b, v59
	v_exp_f32_e32 v25, v25
	v_mul_f32_e32 v26, 0xbfb8aa3b, v69
	v_exp_f32_e32 v26, v26
	v_add_f32_dpp v0, v0, v0 row_half_mirror row_mask:0xf bank_mask:0xf
	v_add_f32_e32 v18, 1.0, v19
	v_add_f32_e32 v19, 1.0, v20
	v_mov_b32_e32 v20, 0x358637bd
	v_rcp_f32_e32 v18, v18
	v_add_f32_dpp v0, v0, v0 row_mirror row_mask:0xf bank_mask:0xf
	v_fmamk_f32 v0, v0, 0x3b800000, v20
	v_mul_f32_e32 v20, 0x4b800000, v0
	v_cmp_gt_f32_e32 vcc, s31, v0
	v_rcp_f32_e32 v19, v19
	v_mul_f32_e32 v27, 0xbfb8aa3b, v73
	v_cndmask_b32_e32 v0, v0, v20, vcc
	v_rsq_f32_e32 v0, v0
	v_mul_f32_e32 v20, 0xbfb8aa3b, v50
	v_exp_f32_e32 v22, v20
	v_pk_mul_f32 v[18:19], v[46:47], v[18:19]
	v_mul_f32_e32 v20, 0x45800000, v0
	v_cndmask_b32_e32 v0, v0, v20, vcc
	v_pk_mul_f32 v[20:21], v[48:49], v[0:1] op_sel_hi:[1,0]
	v_exp_f32_e32 v27, v27
	v_pk_mul_f32 v[20:21], v[14:15], v[20:21]
	v_mul_f32_e32 v28, 0xbfb8aa3b, v77
	v_pk_mul_f32 v[18:19], v[18:19], v[20:21]
	v_add_f32_e32 v20, 1.0, v22
	v_add_f32_e32 v21, 1.0, v23
	v_cvt_pk_bf16_f32 v18, v18, v19
	v_mul_f32_e32 v19, 0xbfb8aa3b, v54
	v_rcp_f32_e32 v20, v20
	v_rcp_f32_e32 v21, v21
	v_exp_f32_e32 v19, v19
	v_pk_mul_f32 v[22:23], v[52:53], v[0:1] op_sel_hi:[1,0]
	v_exp_f32_e32 v28, v28
	v_pk_mul_f32 v[22:23], v[16:17], v[22:23]
	v_pk_mul_f32 v[20:21], v[50:51], v[20:21]
	v_add_f32_e32 v19, 1.0, v19
	v_pk_mul_f32 v[20:21], v[20:21], v[22:23]
	v_rcp_f32_e32 v22, v19
	v_add_f32_e32 v19, 1.0, v24
	v_rcp_f32_e32 v23, v19
	v_mul_f32_e32 v24, 0xbfb8aa3b, v58
	v_exp_f32_e32 v24, v24
	v_cvt_pk_bf16_f32 v19, v20, v21
	v_pk_mul_f32 v[20:21], v[56:57], v[0:1] op_sel_hi:[1,0]
	v_pk_mul_f32 v[22:23], v[54:55], v[22:23]
	v_pk_mul_f32 v[20:21], v[10:11], v[20:21]
	v_mul_f32_e32 v29, 0xbfb8aa3b, v81
	v_pk_mul_f32 v[20:21], v[22:23], v[20:21]
	v_add_f32_e32 v22, 1.0, v24
	v_add_f32_e32 v23, 1.0, v25
	v_cvt_pk_bf16_f32 v20, v20, v21
	v_mul_f32_e32 v21, 0xbfb8aa3b, v68
	v_rcp_f32_e32 v22, v22
	v_rcp_f32_e32 v23, v23
	v_exp_f32_e32 v21, v21
	v_pk_mul_f32 v[24:25], v[60:61], v[0:1] op_sel_hi:[1,0]
	v_exp_f32_e32 v29, v29
	v_pk_mul_f32 v[24:25], v[12:13], v[24:25]
	v_pk_mul_f32 v[22:23], v[58:59], v[22:23]
	v_add_f32_e32 v21, 1.0, v21
	v_pk_mul_f32 v[22:23], v[22:23], v[24:25]
	v_rcp_f32_e32 v24, v21
	v_add_f32_e32 v21, 1.0, v26
	v_rcp_f32_e32 v25, v21
	v_mul_f32_e32 v26, 0xbfb8aa3b, v72
	v_exp_f32_e32 v26, v26
	v_cvt_pk_bf16_f32 v21, v22, v23
	v_pk_mul_f32 v[22:23], v[66:67], v[0:1] op_sel_hi:[1,0]
	v_pk_mul_f32 v[24:25], v[68:69], v[24:25]
	v_pk_mul_f32 v[22:23], v[6:7], v[22:23]
	s_nop 0
	v_pk_mul_f32 v[22:23], v[24:25], v[22:23]
	v_add_f32_e32 v24, 1.0, v26
	v_add_f32_e32 v25, 1.0, v27
	v_cvt_pk_bf16_f32 v22, v22, v23
	v_mul_f32_e32 v23, 0xbfb8aa3b, v76
	v_rcp_f32_e32 v24, v24
	v_rcp_f32_e32 v25, v25
	v_exp_f32_e32 v23, v23
	v_pk_mul_f32 v[26:27], v[70:71], v[0:1] op_sel_hi:[1,0]
	v_pk_mul_f32 v[24:25], v[72:73], v[24:25]
	v_pk_mul_f32 v[26:27], v[8:9], v[26:27]
	v_add_f32_e32 v23, 1.0, v23
	v_pk_mul_f32 v[24:25], v[24:25], v[26:27]
	v_rcp_f32_e32 v26, v23
	v_add_f32_e32 v23, 1.0, v28
	v_rcp_f32_e32 v27, v23
	v_mul_f32_e32 v28, 0xbfb8aa3b, v80
	v_exp_f32_e32 v28, v28
	v_cvt_pk_bf16_f32 v23, v24, v25
	v_pk_mul_f32 v[24:25], v[74:75], v[0:1] op_sel_hi:[1,0]
	v_pk_mul_f32 v[26:27], v[76:77], v[26:27]
	v_pk_mul_f32 v[24:25], v[2:3], v[24:25]
	s_nop 0
	v_pk_mul_f32 v[24:25], v[26:27], v[24:25]
	v_add_f32_e32 v26, 1.0, v28
	v_add_f32_e32 v27, 1.0, v29
	v_rcp_f32_e32 v26, v26
	v_rcp_f32_e32 v27, v27
	v_pk_mul_f32 v[28:29], v[78:79], v[0:1] op_sel_hi:[1,0]
	v_cvt_pk_bf16_f32 v24, v24, v25
	v_pk_mul_f32 v[28:29], v[4:5], v[28:29]
	v_pk_mul_f32 v[26:27], v[80:81], v[26:27]
	s_nop 0
	v_pk_mul_f32 v[26:27], v[26:27], v[28:29]
	s_nop 0
	v_cvt_pk_bf16_f32 v25, v26, v27
	v_lshlrev_b64 v[26:27], 11, v[62:63]
	v_lshl_add_u64 v[26:27], v[44:45], 0, v[26:27]
	global_store_dwordx4 v[26:27], v[18:21], off
	global_store_dwordx4 v[26:27], v[22:25], off offset:16
	s_branch .LBB0_149
